# diff item prologue: second-component Q rows and remaining gain vectors requested with the first load batch
# speedup vs baseline: 1.0013x; 1.0013x over previous
; #define LAS __attribute__((address_space(3)))
; __device__ __forceinline__ unsigned pk2(float lo, float hi) { f32x2 v = {lo, hi}; bf16x2_t b = __builtin_convertvector(v, bf16x2_t); return __builtin_bit_cast(unsigned, b); }
; __device__ __forceinline__ float bflo(unsigned u) { return __uint_as_float(u << 16); }
; __device__ __forceinline__ float bfhi(unsigned u) { return __uint_as_float(u & 0xffff0000u); }
; template <int MODE>
; __device__ __forceinline__ void attn_item(const AttnP& p, int b, int h, int qb, LAS unsigned char* lds) {
;     ...
;     bf16x8 Qf[NC][4];
; #pragma unroll
;     for (int c = 0; c < NC; ++c) {
;         u32x4 raw[4]; float ss = 0.f;
; #pragma unroll
;         for (int ks = 0; ks < 4; ++ks) {
;             raw[ks] = *(const u32x4*)(P + (size_t)(tok0 + qrow) * PP + qcol + c * 64 + ks * 16 + hh * 8);
; #pragma unroll
;             for (int e = 0; e < 4; ++e) { const float lo = bflo(raw[ks][e]), hi = bfhi(raw[ks][e]); ss += lo * lo + hi * hi; }
;         }
;         float sc = 0.125f * LOG2E;
;         if (MODE != 1) { ss += __shfl_xor(ss, 32); sc *= 1.0f / sqrtf(ss * (1.0f / 64.0f) + 1e-6f); }
; #pragma unroll
;         for (int ks = 0; ks < 4; ++ks) {
;             u32x4 o;
; #pragma unroll
;             for (int e = 0; e < 4; ++e) {
;                 float lo = bflo(raw[ks][e]) * sc, hi = bfhi(raw[ks][e]) * sc;
;                 if (MODE != 1) {
;                     const int d = ks * 16 + hh * 8 + 2 * e;
;                     const float* gq = p.qk_gain + ((MODE == 0) ? 0 : 128); const float* gk = gq + 64;
;                     lo *= gq[d] * gk[d]; hi *= gq[d + 1] * gk[d + 1];
;                 }
;                 o[e] = pk2(lo, hi);
;             }
;             Qf[c][ks] = __builtin_bit_cast(bf16x8, o);
;             if (QPARK) *(LAS u32x4*)(lds + QP_OFF + w * 8192 + ((c * 4 + ks) * 64 + lane) * 16) = o;
;         }
;     }
.LBB0_491:
	s_and_b64 vcc, exec, s[0:1]
	s_cbranch_vccz .LBB0_468
	v_mov_b32_e32 v50, v210
	s_ashr_i32 s2, s57, 5
	s_sub_i32 s5, 15, s2
	v_readfirstlane_b32 s0, v50
	s_ashr_i32 s7, s0, 6
	s_lshl_b32 s0, s57, 10
	s_and_b32 s8, s0, 0x7000
	s_lshl_b32 s0, s5, 8
	s_lshl_b32 s3, s7, 5
	v_and_b32_e32 v49, 31, v50
	s_add_i32 s4, s3, s0
	v_or_b32_e32 v228, s4, v49
	s_and_b32 s6, s57, 3
	v_add_u32_e32 v0, s8, v228
	v_mov_b64_e32 v[2:3], s[46:47]
	v_bfe_u32 v48, v50, 5, 1
	v_mad_i64_i32 v[2:3], s[0:1], v0, s76, v[2:3]
	s_lshl_b32 s92, s6, 8
	v_lshl_add_u64 v[2:3], v[2:3], 0, s[92:93]
	v_lshlrev_b32_e32 v206, 4, v48
	v_mov_b32_e32 v207, v1
	v_and_b32_e32 v0, 32, v50
	v_lshl_add_u64 v[32:33], v[2:3], 0, v[206:207]
	global_load_dwordx4 v[52:55], v0, s[40:41] offset:16
	global_load_dwordx4 v[34:37], v0, s[40:41]
	global_load_dwordx4 v[56:59], v0, s[40:41] offset:272
	global_load_dwordx4 v[38:41], v0, s[40:41] offset:256
	global_load_dwordx4 v[60:63], v[32:33], off offset:64
	global_load_dwordx4 v[64:67], v[32:33], off offset:96
	global_load_dwordx4 v[68:71], v[32:33], off
	global_load_dwordx4 v[72:75], v[32:33], off offset:32
	global_load_dwordx4 v[14:17], v0, s[40:41] offset:80
	global_load_dwordx4 v[22:25], v0, s[40:41] offset:64
	global_load_dwordx4 v[76:79], v0, s[40:41] offset:336
	global_load_dwordx4 v[80:83], v0, s[40:41] offset:320
	global_load_dwordx4 v[2:5], v0, s[40:41] offset:144
	global_load_dwordx4 v[10:13], v0, s[40:41] offset:128
	global_load_dwordx4 v[6:9], v0, s[40:41] offset:400
	global_load_dwordx4 v[18:21], v0, s[40:41] offset:384
	global_load_dwordx4 v[130:133], v0, s[40:41] offset:208
	global_load_dwordx4 v[134:137], v0, s[40:41] offset:192
	global_load_dwordx4 v[138:141], v0, s[40:41] offset:464
	global_load_dwordx4 v[142:145], v0, s[40:41] offset:448
	global_load_dwordx4 v[146:149], v[32:33], off offset:192
	global_load_dwordx4 v[150:153], v[32:33], off offset:224
	global_load_dwordx4 v[154:157], v[32:33], off offset:128
	global_load_dwordx4 v[158:161], v[32:33], off offset:160
	s_lshl_b32 s0, s7, 13
	v_and_b32_e32 v51, 63, v50
	s_add_i32 s0, s0, 0
	s_mov_b32 s7, 0xf800000
	s_add_i32 s0, s0, 0x13000
	s_mov_b32 s74, 0xf800000
	s_lshl_b32 s9, s6, 7
	s_waitcnt vmcnt(0)
	v_pk_mul_f32 v[14:15], v[14:15], v[76:77]
	s_waitcnt lgkmcnt(0)
	v_lshlrev_b32_e32 v45, 16, v63
	v_lshlrev_b32_e32 v44, 16, v62
	v_lshlrev_b32_e32 v84, 16, v71
	v_and_b32_e32 v85, 0xffff0000, v71
	v_lshlrev_b32_e32 v86, 16, v70
	v_and_b32_e32 v87, 0xffff0000, v70
	v_lshlrev_b32_e32 v70, 16, v69
	v_and_b32_e32 v71, 0xffff0000, v69
	v_lshlrev_b32_e32 v88, 16, v68
	v_and_b32_e32 v89, 0xffff0000, v68
	v_pk_mul_f32 v[28:29], v[36:37], v[40:41]
	v_pk_mul_f32 v[30:31], v[34:35], v[38:39]
	v_and_b32_e32 v47, 0xffff0000, v63
	v_and_b32_e32 v46, 0xffff0000, v62
	v_lshlrev_b32_e32 v39, 16, v67
	v_lshlrev_b32_e32 v38, 16, v66
	v_and_b32_e32 v37, 0xffff0000, v67
	v_and_b32_e32 v36, 0xffff0000, v66
	v_pk_mul_f32 v[62:63], v[84:85], v[84:85]
	v_pk_mul_f32 v[66:67], v[70:71], v[70:71]
	v_pk_mul_f32 v[96:97], v[88:89], v[88:89]
	v_lshlrev_b32_e32 v43, 16, v65
	v_lshlrev_b32_e32 v42, 16, v64
	v_and_b32_e32 v41, 0xffff0000, v65
	v_and_b32_e32 v40, 0xffff0000, v64
	v_pk_mul_f32 v[64:65], v[86:87], v[86:87]
	v_add_f32_e32 v62, v62, v63
	v_add_f32_e32 v63, v66, v67
	v_add_f32_e32 v66, v96, v97
	v_lshlrev_b32_e32 v92, 16, v72
	v_and_b32_e32 v93, 0xffff0000, v72
	v_add_f32_e32 v63, v66, v63
	v_add_f32_e32 v64, v64, v65
	v_lshlrev_b32_e32 v68, 16, v75
	v_and_b32_e32 v69, 0xffff0000, v75
	v_lshlrev_b32_e32 v90, 16, v74
	v_and_b32_e32 v91, 0xffff0000, v74
	v_lshlrev_b32_e32 v74, 16, v73
	v_and_b32_e32 v75, 0xffff0000, v73
	v_pk_mul_f32 v[104:105], v[92:93], v[92:93]
	v_add_f32_e32 v63, v64, v63
	v_pk_mul_f32 v[102:103], v[74:75], v[74:75]
	v_add_f32_e32 v62, v62, v63
	v_add_f32_e32 v63, v104, v105
	v_pk_mul_f32 v[100:101], v[90:91], v[90:91]
	v_add_f32_e32 v62, v63, v62
	v_add_f32_e32 v63, v102, v103
	v_lshlrev_b32_e32 v94, 16, v60
	v_pk_mul_f32 v[98:99], v[68:69], v[68:69]
	v_and_b32_e32 v95, 0xffff0000, v60
	v_add_f32_e32 v62, v63, v62
	v_add_f32_e32 v63, v100, v101
	v_lshlrev_b32_e32 v72, 16, v61
	v_and_b32_e32 v73, 0xffff0000, v61
	v_pk_mul_f32 v[60:61], v[94:95], v[94:95]
	v_add_f32_e32 v62, v63, v62
	v_add_f32_e32 v63, v98, v99
	v_pk_mul_f32 v[106:107], v[72:73], v[72:73]
	v_add_f32_e32 v62, v63, v62
	v_add_f32_e32 v60, v60, v61
	v_pk_mul_f32 v[34:35], v[46:47], v[46:47]
	v_add_f32_e32 v60, v60, v62
	v_add_f32_e32 v61, v106, v107
	v_pk_fma_f32 v[34:35], v[44:45], v[44:45], v[34:35]
	v_add_f32_e32 v60, v61, v60
	v_pk_mul_f32 v[26:27], v[52:53], v[56:57]
	v_pk_mul_f32 v[52:53], v[40:41], v[40:41]
	v_add_f32_e32 v34, v34, v60
	v_pk_fma_f32 v[52:53], v[42:43], v[42:43], v[52:53]
	v_add_f32_e32 v34, v35, v34
	v_pk_mul_f32 v[56:57], v[36:37], v[36:37]
	v_add_f32_e32 v34, v52, v34
	v_pk_fma_f32 v[56:57], v[38:39], v[38:39], v[56:57]
	v_add_f32_e32 v34, v53, v34
	v_add_f32_e32 v34, v56, v34
	v_add_f32_e32 v52, v57, v34
	ds_bpermute_b32 v53, v226, v52
	v_pk_mul_f32 v[34:35], v[54:55], v[58:59]
	v_lshlrev_b32_e32 v54, 4, v51
	v_add_u32_e32 v207, s0, v54
	v_pk_mul_f32 v[24:25], v[24:25], v[82:83]
	s_waitcnt lgkmcnt(0)
; #define LAS __attribute__((address_space(3)))
; __device__ __forceinline__ unsigned pk2(float lo, float hi) { f32x2 v = {lo, hi}; bf16x2_t b = __builtin_convertvector(v, bf16x2_t); return __builtin_bit_cast(unsigned, b); }
; __device__ __forceinline__ float bflo(unsigned u) { return __uint_as_float(u << 16); }
; __device__ __forceinline__ float bfhi(unsigned u) { return __uint_as_float(u & 0xffff0000u); }
; template <int MODE>
; __device__ __forceinline__ void attn_item(const AttnP& p, int b, int h, int qb, LAS unsigned char* lds) {
;     ...
;     for (int c = 0; c < NC; ++c) {
;         u32x4 raw[4]; float ss = 0.f;
; #pragma unroll
;         for (int ks = 0; ks < 4; ++ks) {
;             raw[ks] = *(const u32x4*)(P + (size_t)(tok0 + qrow) * PP + qcol + c * 64 + ks * 16 + hh * 8);
; #pragma unroll
;             for (int e = 0; e < 4; ++e) { const float lo = bflo(raw[ks][e]), hi = bfhi(raw[ks][e]); ss += lo * lo + hi * hi; }
;         }
;         float sc = 0.125f * LOG2E;
;         if (MODE != 1) { ss += __shfl_xor(ss, 32); sc *= 1.0f / sqrtf(ss * (1.0f / 64.0f) + 1e-6f); }
; #pragma unroll
;         for (int ks = 0; ks < 4; ++ks) {
;             u32x4 o;
; #pragma unroll
;             for (int e = 0; e < 4; ++e) {
;                 float lo = bflo(raw[ks][e]) * sc, hi = bfhi(raw[ks][e]) * sc;
;                 if (MODE != 1) {
;                     const int d = ks * 16 + hh * 8 + 2 * e;
;                     const float* gq = p.qk_gain + ((MODE == 0) ? 0 : 128); const float* gk = gq + 64;
;                     lo *= gq[d] * gk[d]; hi *= gq[d + 1] * gk[d + 1];
;                 }
;                 o[e] = pk2(lo, hi);
;             }
;             Qf[c][ks] = __builtin_bit_cast(bf16x8, o);
;             if (QPARK) *(LAS u32x4*)(lds + QP_OFF + w * 8192 + ((c * 4 + ks) * 64 + lane) * 16) = o;
	v_add_f32_e32 v52, v52, v53
	v_fmamk_f32 v52, v52, 0x3c800000, v211
	v_mul_f32_e32 v53, 0x4f800000, v52
	v_cmp_gt_f32_e32 vcc, s7, v52
	v_pk_mul_f32 v[10:11], v[10:11], v[18:19]
	v_pk_mul_f32 v[16:17], v[16:17], v[78:79]
	v_cndmask_b32_e32 v76, v52, v53, vcc
	v_mov_b64_e32 v[52:53], v[130:131]
	v_mov_b64_e32 v[54:55], v[132:133]
	v_mov_b64_e32 v[56:57], v[134:135]
	v_mov_b64_e32 v[58:59], v[136:137]
	v_mov_b64_e32 v[60:61], v[138:139]
	v_mov_b64_e32 v[62:63], v[140:141]
	v_mov_b64_e32 v[64:65], v[142:143]
	v_mov_b64_e32 v[66:67], v[144:145]
	v_sqrt_f32_e32 v77, v76
	v_pk_mul_f32 v[22:23], v[22:23], v[80:81]
	v_pk_mul_f32 v[12:13], v[12:13], v[20:21]
	v_add_u32_e32 v0, -1, v77
	v_fma_f32 v82, -v0, v77, v76
	v_cmp_ge_f32_e64 s[0:1], 0, v82
	v_add_u32_e32 v82, 1, v77
	s_nop 0
	v_cndmask_b32_e64 v0, v77, v0, s[0:1]
	v_fma_f32 v77, -v82, v77, v76
	v_cmp_lt_f32_e64 s[0:1], 0, v77
	s_nop 1
	v_cndmask_b32_e64 v0, v0, v82, s[0:1]
	v_mul_f32_e32 v77, 0x37800000, v0
	v_cndmask_b32_e32 v0, v0, v77, vcc
	v_cmp_class_f32_e32 vcc, v76, v212
	s_nop 1
	v_cndmask_b32_e32 v0, v0, v76, vcc
	v_div_scale_f32 v76, s[0:1], v0, v0, 1.0
	v_rcp_f32_e32 v77, v76
	s_nop 0
	v_fma_f32 v18, -v76, v77, 1.0
	v_fmac_f32_e32 v77, v18, v77
	v_div_scale_f32 v18, vcc, 1.0, v0, 1.0
	v_mul_f32_e32 v19, v18, v77
	v_fma_f32 v78, -v76, v19, v18
	v_fmac_f32_e32 v19, v78, v77
	v_fma_f32 v18, -v76, v19, v18
	v_div_fmas_f32 v18, v18, v77, v19
	v_div_fixup_f32 v0, v18, v0, 1.0
	v_mul_f32_e32 v0, 0x3e38aa3b, v0
	v_pk_mul_f32 v[18:19], v[0:1], v[88:89] op_sel_hi:[0,1]
	v_pk_mul_f32 v[18:19], v[30:31], v[18:19]
	s_nop 0
	v_cvt_pk_bf16_f32 v162, v18, v19
	v_pk_mul_f32 v[18:19], v[0:1], v[70:71] op_sel_hi:[0,1]
	v_pk_mul_f32 v[18:19], v[28:29], v[18:19]
	s_nop 0
	v_cvt_pk_bf16_f32 v163, v18, v19
	v_pk_mul_f32 v[18:19], v[0:1], v[86:87] op_sel_hi:[0,1]
	v_pk_mul_f32 v[18:19], v[26:27], v[18:19]
	s_nop 0
	v_cvt_pk_bf16_f32 v164, v18, v19
	v_pk_mul_f32 v[18:19], v[0:1], v[84:85] op_sel_hi:[0,1]
	v_pk_mul_f32 v[18:19], v[34:35], v[18:19]
	s_nop 0
	v_cvt_pk_bf16_f32 v165, v18, v19
	v_pk_mul_f32 v[18:19], v[0:1], v[92:93] op_sel_hi:[0,1]
	v_pk_mul_f32 v[18:19], v[22:23], v[18:19]
	ds_write_b128 v207, v[162:165]
	v_cvt_pk_bf16_f32 v166, v18, v19
	v_pk_mul_f32 v[18:19], v[0:1], v[74:75] op_sel_hi:[0,1]
	v_pk_mul_f32 v[18:19], v[18:19], v[24:25]
	s_nop 0
	v_cvt_pk_bf16_f32 v167, v18, v19
	v_pk_mul_f32 v[18:19], v[0:1], v[90:91] op_sel_hi:[0,1]
	v_pk_mul_f32 v[18:19], v[18:19], v[14:15]
	s_nop 0
	v_cvt_pk_bf16_f32 v168, v18, v19
	v_pk_mul_f32 v[18:19], v[0:1], v[68:69] op_sel_hi:[0,1]
	v_pk_mul_f32 v[18:19], v[18:19], v[16:17]
	v_pk_mul_f32 v[68:69], v[2:3], v[6:7]
	v_cvt_pk_bf16_f32 v169, v18, v19
	v_pk_mul_f32 v[18:19], v[0:1], v[94:95] op_sel_hi:[0,1]
	v_pk_mul_f32 v[18:19], v[18:19], v[10:11]
	ds_write_b128 v207, v[166:169] offset:1024
	v_cvt_pk_bf16_f32 v170, v18, v19
	v_pk_mul_f32 v[18:19], v[0:1], v[72:73] op_sel_hi:[0,1]
	v_pk_mul_f32 v[18:19], v[18:19], v[12:13]
	s_nop 0
	v_cvt_pk_bf16_f32 v171, v18, v19
	v_mov_b32_e32 v18, v44
	v_mov_b32_e32 v19, v46
	v_pk_mul_f32 v[18:19], v[0:1], v[18:19] op_sel_hi:[0,1]
	v_pk_mul_f32 v[2:3], v[18:19], v[68:69]
	v_mov_b32_e32 v46, v45
	v_cvt_pk_bf16_f32 v172, v2, v3
	v_pk_mul_f32 v[2:3], v[0:1], v[46:47] op_sel_hi:[0,1]
	v_pk_mul_f32 v[44:45], v[4:5], v[8:9]
	s_waitcnt vmcnt(0)
	v_pk_mul_f32 v[46:47], v[56:57], v[64:65]
	v_pk_mul_f32 v[2:3], v[2:3], v[44:45]
	s_nop 0
	v_cvt_pk_bf16_f32 v173, v2, v3
	v_mov_b32_e32 v2, v42
	v_mov_b32_e32 v3, v40
	v_pk_mul_f32 v[2:3], v[0:1], v[2:3] op_sel_hi:[0,1]
	v_pk_mul_f32 v[2:3], v[2:3], v[46:47]
	v_mov_b32_e32 v40, v43
	v_cvt_pk_bf16_f32 v174, v2, v3
	v_pk_mul_f32 v[2:3], v[0:1], v[40:41] op_sel_hi:[0,1]
	v_pk_mul_f32 v[40:41], v[58:59], v[66:67]
	v_pk_mul_f32 v[42:43], v[52:53], v[60:61]
	v_pk_mul_f32 v[2:3], v[2:3], v[40:41]
	v_pk_mul_f32 v[52:53], v[54:55], v[62:63]
	v_cvt_pk_bf16_f32 v175, v2, v3
	v_mov_b32_e32 v2, v38
	v_mov_b32_e32 v3, v36
	v_pk_mul_f32 v[2:3], v[0:1], v[2:3] op_sel_hi:[0,1]
	v_pk_mul_f32 v[2:3], v[2:3], v[42:43]
	v_mov_b32_e32 v36, v39
	v_cvt_pk_bf16_f32 v176, v2, v3
	v_pk_mul_f32 v[2:3], v[0:1], v[36:37] op_sel_hi:[0,1]
	v_pk_mul_f32 v[2:3], v[2:3], v[52:53]
	ds_write_b128 v207, v[170:173] offset:2048
	v_cvt_pk_bf16_f32 v177, v2, v3
	ds_write_b128 v207, v[174:177] offset:3072
	v_mov_b64_e32 v[2:3], v[146:147]
	v_mov_b64_e32 v[4:5], v[148:149]
	v_mov_b64_e32 v[6:7], v[150:151]
	v_mov_b64_e32 v[8:9], v[152:153]
	v_mov_b64_e32 v[18:19], v[154:155]
	v_mov_b64_e32 v[20:21], v[156:157]
	v_mov_b64_e32 v[36:37], v[158:159]
	v_mov_b64_e32 v[38:39], v[160:161]
	s_waitcnt vmcnt(0) lgkmcnt(0)
; #define LAS __attribute__((address_space(3)))
; __device__ __forceinline__ unsigned pk2(float lo, float hi) { f32x2 v = {lo, hi}; bf16x2_t b = __builtin_convertvector(v, bf16x2_t); return __builtin_bit_cast(unsigned, b); }
; __device__ __forceinline__ float bflo(unsigned u) { return __uint_as_float(u << 16); }
; __device__ __forceinline__ float bfhi(unsigned u) { return __uint_as_float(u & 0xffff0000u); }
; template <int MODE>
; __device__ __forceinline__ void attn_item(const AttnP& p, int b, int h, int qb, LAS unsigned char* lds) {
;     ...
;     for (int c = 0; c < NC; ++c) {
;         u32x4 raw[4]; float ss = 0.f;
; #pragma unroll
;         for (int ks = 0; ks < 4; ++ks) {
;             raw[ks] = *(const u32x4*)(P + (size_t)(tok0 + qrow) * PP + qcol + c * 64 + ks * 16 + hh * 8);
; #pragma unroll
;             for (int e = 0; e < 4; ++e) { const float lo = bflo(raw[ks][e]), hi = bfhi(raw[ks][e]); ss += lo * lo + hi * hi; }
;         }
;         float sc = 0.125f * LOG2E;
;         if (MODE != 1) { ss += __shfl_xor(ss, 32); sc *= 1.0f / sqrtf(ss * (1.0f / 64.0f) + 1e-6f); }
; #pragma unroll
;         for (int ks = 0; ks < 4; ++ks) {
;             u32x4 o;
; #pragma unroll
;             for (int e = 0; e < 4; ++e) {
;                 float lo = bflo(raw[ks][e]) * sc, hi = bfhi(raw[ks][e]) * sc;
;                 if (MODE != 1) {
;                     const int d = ks * 16 + hh * 8 + 2 * e;
;                     const float* gq = p.qk_gain + ((MODE == 0) ? 0 : 128); const float* gk = gq + 64;
;                     lo *= gq[d] * gk[d]; hi *= gq[d + 1] * gk[d + 1];
;                 }
;                 o[e] = pk2(lo, hi);
;             }
;             Qf[c][ks] = __builtin_bit_cast(bf16x8, o);
;             if (QPARK) *(LAS u32x4*)(lds + QP_OFF + w * 8192 + ((c * 4 + ks) * 64 + lane) * 16) = o;
;         }
;     }
;     if (MODE == 0) { LAS float* tab = (LAS float*)(lds + TAB_OFF); if (tid < 256) tab[tid] = p.biasT[h * 256 + tid]; }
	v_lshlrev_b32_e32 v94, 16, v2
	v_and_b32_e32 v95, 0xffff0000, v2
	v_lshlrev_b32_e32 v64, 16, v21
	v_and_b32_e32 v65, 0xffff0000, v21
	v_lshlrev_b32_e32 v72, 16, v19
	v_and_b32_e32 v73, 0xffff0000, v19
	v_lshlrev_b32_e32 v76, 16, v18
	v_and_b32_e32 v77, 0xffff0000, v18
	v_pk_mul_f32 v[66:67], v[64:65], v[64:65]
	v_lshlrev_b32_e32 v70, 16, v20
	v_and_b32_e32 v71, 0xffff0000, v20
	v_pk_mul_f32 v[74:75], v[72:73], v[72:73]
	v_pk_mul_f32 v[18:19], v[76:77], v[76:77]
	v_pk_mul_f32 v[20:21], v[70:71], v[70:71]
	v_add_f32_e32 v0, v66, v67
	v_add_f32_e32 v66, v74, v75
	v_add_f32_e32 v18, v18, v19
	v_lshlrev_b32_e32 v88, 16, v36
	v_and_b32_e32 v89, 0xffff0000, v36
	v_add_f32_e32 v18, v18, v66
	v_add_f32_e32 v19, v20, v21
	v_lshlrev_b32_e32 v84, 16, v37
	v_and_b32_e32 v85, 0xffff0000, v37
	v_pk_mul_f32 v[36:37], v[88:89], v[88:89]
	v_add_f32_e32 v18, v19, v18
	v_lshlrev_b32_e32 v82, 16, v38
	v_and_b32_e32 v83, 0xffff0000, v38
	v_pk_mul_f32 v[86:87], v[84:85], v[84:85]
	v_add_f32_e32 v0, v0, v18
	v_add_f32_e32 v18, v36, v37
	v_lshlrev_b32_e32 v78, 16, v39
	v_and_b32_e32 v79, 0xffff0000, v39
	v_pk_mul_f32 v[38:39], v[82:83], v[82:83]
	v_add_f32_e32 v0, v18, v0
	v_add_f32_e32 v18, v86, v87
	v_pk_mul_f32 v[80:81], v[78:79], v[78:79]
	v_add_f32_e32 v0, v18, v0
	v_add_f32_e32 v18, v38, v39
	v_lshlrev_b32_e32 v90, 16, v3
	v_and_b32_e32 v91, 0xffff0000, v3
	v_pk_mul_f32 v[2:3], v[94:95], v[94:95]
	v_add_f32_e32 v0, v18, v0
	v_add_f32_e32 v18, v80, v81
	v_and_b32_e32 v55, 0xffff0000, v5
	v_and_b32_e32 v54, 0xffff0000, v4
	v_pk_mul_f32 v[92:93], v[90:91], v[90:91]
	v_add_f32_e32 v0, v18, v0
	v_add_f32_e32 v2, v2, v3
	v_lshlrev_b32_e32 v33, 16, v5
	v_lshlrev_b32_e32 v32, 16, v4
	v_pk_mul_f32 v[4:5], v[54:55], v[54:55]
	v_add_f32_e32 v0, v2, v0
	v_add_f32_e32 v2, v92, v93
	v_pk_fma_f32 v[4:5], v[32:33], v[32:33], v[4:5]
	v_lshlrev_b32_e32 v57, 16, v7
	v_lshlrev_b32_e32 v56, 16, v6
	v_and_b32_e32 v7, 0xffff0000, v7
	v_and_b32_e32 v6, 0xffff0000, v6
	v_add_f32_e32 v0, v2, v0
	v_pk_mul_f32 v[58:59], v[6:7], v[6:7]
	v_add_f32_e32 v0, v4, v0
	v_pk_fma_f32 v[58:59], v[56:57], v[56:57], v[58:59]
	v_lshlrev_b32_e32 v61, 16, v9
	v_lshlrev_b32_e32 v60, 16, v8
	v_and_b32_e32 v9, 0xffff0000, v9
	v_and_b32_e32 v8, 0xffff0000, v8
	v_add_f32_e32 v0, v5, v0
	v_pk_mul_f32 v[62:63], v[8:9], v[8:9]
	v_add_f32_e32 v0, v58, v0
	v_pk_fma_f32 v[62:63], v[60:61], v[60:61], v[62:63]
	v_add_f32_e32 v0, v59, v0
	v_add_f32_e32 v0, v62, v0
	v_add_f32_e32 v0, v63, v0
	ds_bpermute_b32 v2, v226, v0
	s_waitcnt lgkmcnt(0)
	v_add_f32_e32 v0, v0, v2
	v_fmamk_f32 v0, v0, 0x3c800000, v211
	v_mul_f32_e32 v2, 0x4f800000, v0
	v_cmp_gt_f32_e32 vcc, s7, v0
	s_nop 1
	v_cndmask_b32_e32 v0, v0, v2, vcc
	v_sqrt_f32_e32 v2, v0
	s_nop 0
	v_add_u32_e32 v3, -1, v2
	v_fma_f32 v4, -v3, v2, v0
	v_cmp_ge_f32_e64 s[0:1], 0, v4
	v_add_u32_e32 v4, 1, v2
	s_nop 0
	v_cndmask_b32_e64 v3, v2, v3, s[0:1]
	v_fma_f32 v2, -v4, v2, v0
	v_cmp_lt_f32_e64 s[0:1], 0, v2
	s_nop 1
	v_cndmask_b32_e64 v2, v3, v4, s[0:1]
	v_mul_f32_e32 v3, 0x37800000, v2
	v_cndmask_b32_e32 v2, v2, v3, vcc
	v_cmp_class_f32_e32 vcc, v0, v212
	s_nop 1
	v_cndmask_b32_e32 v0, v2, v0, vcc
	v_div_scale_f32 v2, s[0:1], v0, v0, 1.0
	v_rcp_f32_e32 v3, v2
	s_movk_i32 s0, 0x100
	v_fma_f32 v4, -v2, v3, 1.0
	v_fmac_f32_e32 v3, v4, v3
	v_div_scale_f32 v4, vcc, 1.0, v0, 1.0
	v_mul_f32_e32 v5, v4, v3
	v_fma_f32 v18, -v2, v5, v4
	v_fmac_f32_e32 v5, v18, v3
	v_fma_f32 v2, -v2, v5, v4
	v_div_fmas_f32 v2, v2, v3, v5
	v_div_fixup_f32 v0, v2, v0, 1.0
	v_mul_f32_e32 v0, 0x3e38aa3b, v0
	v_pk_mul_f32 v[2:3], v[0:1], v[76:77] op_sel_hi:[0,1]
	v_pk_mul_f32 v[4:5], v[0:1], v[72:73] op_sel_hi:[0,1]
	v_pk_mul_f32 v[2:3], v[30:31], v[2:3]
	v_pk_mul_f32 v[4:5], v[28:29], v[4:5]
	v_cvt_pk_bf16_f32 v2, v2, v3
	v_cvt_pk_bf16_f32 v3, v4, v5
	v_pk_mul_f32 v[4:5], v[0:1], v[70:71] op_sel_hi:[0,1]
	v_pk_mul_f32 v[18:19], v[0:1], v[64:65] op_sel_hi:[0,1]
	v_pk_mul_f32 v[4:5], v[26:27], v[4:5]
	v_pk_mul_f32 v[18:19], v[34:35], v[18:19]
	v_cvt_pk_bf16_f32 v4, v4, v5
	v_cvt_pk_bf16_f32 v5, v18, v19
	ds_write_b128 v207, v[2:5] offset:4096
	v_pk_mul_f32 v[2:3], v[0:1], v[88:89] op_sel_hi:[0,1]
	v_pk_mul_f32 v[4:5], v[0:1], v[84:85] op_sel_hi:[0,1]
	v_pk_mul_f32 v[2:3], v[22:23], v[2:3]
	v_pk_mul_f32 v[4:5], v[24:25], v[4:5]
	v_cvt_pk_bf16_f32 v2, v2, v3
	v_cvt_pk_bf16_f32 v3, v4, v5
	v_pk_mul_f32 v[4:5], v[0:1], v[82:83] op_sel_hi:[0,1]
	v_pk_mul_f32 v[4:5], v[14:15], v[4:5]
	v_pk_mul_f32 v[14:15], v[0:1], v[78:79] op_sel_hi:[0,1]
	v_pk_mul_f32 v[14:15], v[16:17], v[14:15]
	v_cvt_pk_bf16_f32 v4, v4, v5
	v_cvt_pk_bf16_f32 v5, v14, v15
	ds_write_b128 v207, v[2:5] offset:5120
	v_pk_mul_f32 v[2:3], v[0:1], v[94:95] op_sel_hi:[0,1]
	v_pk_mul_f32 v[4:5], v[0:1], v[90:91] op_sel_hi:[0,1]
	v_pk_mul_f32 v[2:3], v[10:11], v[2:3]
	v_pk_mul_f32 v[4:5], v[12:13], v[4:5]
	v_cvt_pk_bf16_f32 v2, v2, v3
	v_cvt_pk_bf16_f32 v3, v4, v5
	v_mov_b32_e32 v4, v32
	v_mov_b32_e32 v5, v54
	v_mov_b32_e32 v54, v33
	v_pk_mul_f32 v[4:5], v[0:1], v[4:5] op_sel_hi:[0,1]
	v_pk_mul_f32 v[10:11], v[0:1], v[54:55] op_sel_hi:[0,1]
	v_pk_mul_f32 v[4:5], v[68:69], v[4:5]
	v_pk_mul_f32 v[10:11], v[44:45], v[10:11]
	v_cvt_pk_bf16_f32 v4, v4, v5
	v_cvt_pk_bf16_f32 v5, v10, v11
	ds_write_b128 v207, v[2:5] offset:6144
	v_mov_b32_e32 v2, v56
	v_mov_b32_e32 v3, v6
	v_mov_b32_e32 v6, v57
	v_pk_mul_f32 v[2:3], v[0:1], v[2:3] op_sel_hi:[0,1]
	v_pk_mul_f32 v[4:5], v[0:1], v[6:7] op_sel_hi:[0,1]
	v_pk_mul_f32 v[2:3], v[46:47], v[2:3]
	v_pk_mul_f32 v[4:5], v[40:41], v[4:5]
	v_cvt_pk_bf16_f32 v2, v2, v3
	v_cvt_pk_bf16_f32 v3, v4, v5
	v_mov_b32_e32 v4, v60
	v_mov_b32_e32 v5, v8
	v_mov_b32_e32 v8, v61
	v_pk_mul_f32 v[4:5], v[0:1], v[4:5] op_sel_hi:[0,1]
	v_pk_mul_f32 v[6:7], v[0:1], v[8:9] op_sel_hi:[0,1]
	v_pk_mul_f32 v[4:5], v[42:43], v[4:5]
	v_pk_mul_f32 v[6:7], v[52:53], v[6:7]
	v_cvt_pk_bf16_f32 v4, v4, v5
	v_cvt_pk_bf16_f32 v5, v6, v7
	v_cmp_gt_i32_e32 vcc, s0, v50
	ds_write_b128 v207, v[2:5] offset:7168
	s_and_saveexec_b64 s[0:1], vcc
	s_cbranch_execz .LBB0_494
	v_lshl_add_u32 v2, s6, 8, v50
	v_ashrrev_i32_e32 v3, 31, v2
	v_lshl_add_u64 v[2:3], v[2:3], 2, s[42:43]
	global_load_dword v0, v[2:3], off
	v_lshl_add_u32 v2, v50, 2, 0
	v_add_u32_e32 v2, 0x12a00, v2
	s_waitcnt vmcnt(0) lgkmcnt(0)
	ds_write_b32 v2, v0
